# mix2: next chunk's Q tile prefetched into registers late in the current chunk (was loaded and drained at loop top)
# baseline (speedup 1.0000x reference)
; __device__ void mix_sweep(const Params& P, LAS unsigned char* lds, int tok0, int pos0, int seqlen, int hd, int dir, bool state_only, bool final_pass,
;                           f32x4 (&Cacc)[9], float& m_state, float& aseg_sum, float lgam) {
;     ...
;     { const int c = dir ? 7 : 0; const int tok = tok0 + c * 128;
; #pragma unroll
;       for (int which = 1; which < 3; ++which) { const int cb = which == 0 ? qcol : (which == 1 ? kcol : vcolg);
; #pragma unroll
;           for (int it = 0; it < 4; ++it) { const int item = tid + 512 * it, r = item >> 4, ch = item & 15; t[which][it] = *(const u32x4*)(proj + (size_t)(tok + r) * NPROJ + cb + 8 * ch); } } }
;     for (int ci = 0; ci < 8; ++ci) {
;         const int c = dir ? 7 - ci : ci; const int tok = tok0 + c * 128;
;         __syncthreads();
;         int tl = tid; asm volatile("" : "+v"(tl));
;         if (!state_only) {
; #pragma unroll
;             for (int it = 0; it < 4; ++it) { const int item = tl + 512 * it, r = item >> 4, ch = item & 15; t[0][it] = *(const u32x4*)(proj + (size_t)(tok + r) * NPROJ + qcol + 8 * ch); } }
.LBB0_96:
	s_and_b64 s[14:15], s[8:9], exec
	v_and_b32_e32 v0, 0x78, v0
	s_cselect_b32 s14, 0, 0x380
	v_lshlrev_b32_e32 v0, 1, v0
	s_or_b32 s14, s14, s79
	s_waitcnt lgkmcnt(2)
	v_lshl_add_u64 v[2:3], s[22:23], 0, v[0:1]
	v_ashrrev_i32_e32 v0, 4, v161
	v_add_u32_e32 v40, s14, v0
	v_add_u32_e32 v0, 0x200, v161
	v_ashrrev_i32_e32 v0, 4, v0
	v_add_u32_e32 v42, s14, v0
	v_add_u32_e32 v0, 0x400, v161
	v_ashrrev_i32_e32 v0, 4, v0
	v_add_u32_e32 v50, s14, v0
	v_add_u32_e32 v0, 0x600, v161
	v_ashrrev_i32_e32 v0, 4, v0
	v_add_u32_e32 v52, s14, v0
	v_ashrrev_i32_e32 v41, 31, v40
	s_lshl_b32 s38, s80, 1
	v_ashrrev_i32_e32 v43, 31, v42
	v_ashrrev_i32_e32 v51, 31, v50
	v_ashrrev_i32_e32 v53, 31, v52
	s_lshl_b32 s14, s81, 1
	s_mov_b32 s15, s39
	v_lshlrev_b64 v[56:57], 13, v[40:41]
	v_lshl_add_u64 v[48:49], v[2:3], 0, s[38:39]
	v_lshlrev_b64 v[58:59], 13, v[42:43]
	v_lshlrev_b64 v[64:65], 13, v[50:51]
	v_lshlrev_b64 v[66:67], 13, v[52:53]
	v_lshl_add_u64 v[2:3], v[2:3], 0, s[14:15]
	v_lshl_add_u64 v[40:41], v[48:49], 0, v[56:57]
	v_lshl_add_u64 v[44:45], v[48:49], 0, v[58:59]
	v_lshl_add_u64 v[50:51], v[48:49], 0, v[64:65]
	v_lshl_add_u64 v[52:53], v[48:49], 0, v[66:67]
	v_lshl_add_u64 v[56:57], v[2:3], 0, v[56:57]
	v_lshl_add_u64 v[60:61], v[2:3], 0, v[58:59]
	v_lshl_add_u64 v[64:65], v[2:3], 0, v[64:65]
	global_load_dwordx4 v[40:43], v[40:41], off
	s_nop 0
	global_load_dwordx4 v[44:47], v[44:45], off
	s_nop 0
	global_load_dwordx4 v[48:51], v[50:51], off
	s_nop 0
	global_load_dwordx4 v[52:55], v[52:53], off
	s_nop 0
	global_load_dwordx4 v[56:59], v[56:57], off
	s_nop 0
	global_load_dwordx4 v[60:63], v[60:61], off
	v_lshl_add_u64 v[2:3], v[2:3], 0, v[66:67]
	global_load_dwordx4 v[64:67], v[64:65], off
	s_nop 0
	global_load_dwordx4 v[68:71], v[2:3], off
	v_lshlrev_b32_e32 v79, 2, v161
	s_add_i32 s15, 0, 0x22000
	v_add_u32_e32 v182, s15, v79
	s_add_i32 s15, 0, 0x22200
	v_lshlrev_b32_e32 v0, 4, v73
	v_add_u32_e32 v183, s15, v79
	v_add_u32_e32 v190, s15, v0
	v_readlane_b32 s15, v253, 49
	s_add_i32 s19, 0, 0x22400
	v_add_u32_e32 v184, s19, v79
	v_add_u32_e32 v194, s15, v75
	s_add_i32 s15, 0, 0x1a000
	v_add_u32_e32 v195, s15, v75
	v_readlane_b32 s15, v253, 50
	s_add_i32 s19, 0, 0x22600
	s_add_i32 s46, 0, 0x22800
	v_add_u32_e32 v196, s15, v75
	s_add_i32 s15, 0, 0x1c000
	v_add_u32_e32 v197, s15, v75
	v_readlane_b32 s15, v253, 51
	v_lshlrev_b32_e32 v189, 2, v73
	v_mov_b32_e32 v73, v1
	v_add_u32_e32 v198, s15, v75
	s_add_i32 s15, 0, 0x1e000
	v_add_u32_e32 v199, s15, v75
	v_readlane_b32 s15, v253, 52
	s_add_i32 s85, 0, 0x10000
	s_mov_b32 s7, 0
	v_add_u32_e32 v200, s15, v75
	v_readlane_b32 s15, v253, 53
	s_mov_b32 s83, 1
	v_add_u32_e32 v185, s19, v79
	v_add_u32_e32 v247, s15, v75
	s_add_i32 s15, 0, 0x12000
	v_add_u32_e32 v248, s15, v75
	v_readlane_b32 s15, v253, 54
	v_add_u32_e32 v187, s46, v79
	v_cmp_eq_u32_e64 s[46:47], 0, v161
	v_add_u32_e32 v249, s15, v75
	s_add_i32 s15, 0, 0x14000
	v_add_u32_e32 v250, s15, v75
	v_readlane_b32 s15, v253, 55
	v_lshl_or_b32 v219, s16, 4, v169
	s_add_i32 s84, s17, 0
	v_add_u32_e32 v251, s15, v75
	s_add_i32 s15, 0, 0x16000
	v_add_u32_e32 v252, s15, v75
	v_readlane_b32 s15, v253, 56
	v_add_u32_e32 v191, 0, v78
	v_lshl_add_u32 v192, v72, 2, s19
	v_lshl_add_u64 v[2:3], s[2:3], 0, v[72:73]
	v_lshl_add_u64 v[152:153], s[4:5], 0, v[72:73]
	v_lshl_add_u64 v[154:155], s[94:95], 0, v[0:1]
	v_add_u32_e32 v193, s18, v75
	v_or_b32_e32 v201, 2, v189
	v_or_b32_e32 v202, 3, v189
	v_or_b32_e32 v204, 16, v189
	v_or_b32_e32 v205, 17, v189
	v_or_b32_e32 v206, 18, v189
	v_or_b32_e32 v207, 19, v189
	v_or_b32_e32 v222, 32, v189
	v_or_b32_e32 v223, 33, v189
	v_or_b32_e32 v224, 34, v189
	v_or_b32_e32 v225, 35, v189
	v_or_b32_e32 v226, 48, v189
	v_or_b32_e32 v227, 49, v189
	v_or_b32_e32 v228, 50, v189
	v_or_b32_e32 v229, 51, v189
	v_or_b32_e32 v230, 64, v189
	v_or_b32_e32 v231, 0x41, v189
	v_or_b32_e32 v232, 0x42, v189
	v_or_b32_e32 v233, 0x43, v189
	v_or_b32_e32 v234, 0x50, v189
	v_or_b32_e32 v235, 0x51, v189
	v_or_b32_e32 v236, 0x52, v189
	v_or_b32_e32 v237, 0x53, v189
	v_or_b32_e32 v238, 0x60, v189
	v_or_b32_e32 v239, 0x61, v189
	v_or_b32_e32 v240, 0x62, v189
	v_or_b32_e32 v241, 0x63, v189
	v_or_b32_e32 v242, 0x70, v189
	v_or_b32_e32 v243, 0x71, v189
	v_or_b32_e32 v244, 0x72, v189
	v_or_b32_e32 v245, 0x73, v189
	v_add_u32_e32 v246, s85, v75
	v_add_u32_e32 v211, s15, v75
	v_add_u32_e32 v164, 0, v79
	s_mov_b32 s86, 6
	s_movk_i32 s87, 0xd000
	v_add_u32_e32 v165, 0, v76
	v_add_u32_e32 v166, 0, v77
	v_add_u32_e32 v167, 0, v74
	v_readlane_b32 s88, v253, 57
	v_lshrrev_b32_e32 v80, 6, v161
	v_lshlrev_b32_e32 v80, 6, v80
	v_mov_b32_e32 v81, 0
	v_lshl_add_u64 v[82:83], v[154:155], 0, v[80:81]
	global_load_dwordx4 v[84:87], v[82:83], off
	v_bfe_u32 v81, v161, 4, 2
	v_lshl_add_u32 v80, v81, 4, v80
	v_add_u32_e32 v80, 0x25a80, v80
	s_waitcnt vmcnt(0)
	ds_write_b128 v80, v[84:87]
	s_mov_b32 s32, s7
	s_xor_b32 s89, s32, 0x380
	s_cmp_lg_u64 s[8:9], 0
	s_cselect_b32 s32, s32, s89
	s_add_i32 s32, s32, s79
	v_ashrrev_i32_e32 v194, 4, v161
	v_lshlrev_b32_e32 v198, 4, v161
	v_add_u32_e32 v194, s32, v194
	v_and_b32_e32 v198, 0xf0, v198
	v_ashrrev_i32_e32 v195, 31, v194
	v_mov_b32_e32 v199, 0
	v_lshlrev_b64 v[194:195], 13, v[194:195]
	v_lshl_add_u64 v[198:199], s[36:37], 0, v[198:199]
	v_mov_b32_e32 v242, 0x40000
	v_mov_b32_e32 v243, 0
	v_lshl_add_u64 v[194:195], v[198:199], 0, v[194:195]
	v_lshl_add_u64 v[198:199], v[194:195], 0, v[242:243]
	v_lshl_add_u64 v[244:245], v[198:199], 0, v[242:243]
	v_lshl_add_u64 v[154:155], v[244:245], 0, v[242:243]
	s_nop 0
	global_load_dwordx4 v[194:197], v[194:195], off
	s_nop 0
	global_load_dwordx4 v[198:201], v[198:199], off
	s_nop 0
	global_load_dwordx4 v[242:245], v[244:245], off
	s_nop 0
	global_load_dword v202, v[154:155], off offset:8
	s_nop 0
	global_load_dword v186, v[154:155], off offset:12
	s_nop 0
	global_load_dwordx2 v[154:155], v[154:155], off
	s_branch .LBB0_98
; #define LAS __attribute__((address_space(3)))
; __device__ __forceinline__ unsigned cvt_pk_bf16(float lo, float hi) { unsigned r; asm volatile("v_cvt_pk_bf16_f32 %0, %1, %2" : "=v"(r) : "v"(lo), "v"(hi)); return r; }
; __device__ void mix_sweep(const Params& P, LAS unsigned char* lds, int tok0, int pos0, int seqlen, int hd, int dir, bool state_only, bool final_pass,
;                           f32x4 (&Cacc)[9], float& m_state, float& aseg_sum, float lgam) {
;     ...
;         const int c = dir ? 7 - ci : ci; const int tok = tok0 + c * 128;
;         __syncthreads();
;         int tl = tid; asm volatile("" : "+v"(tl));
;         if (!state_only) {
; #pragma unroll
;             for (int it = 0; it < 4; ++it) { const int item = tl + 512 * it, r = item >> 4, ch = item & 15; t[0][it] = *(const u32x4*)(proj + (size_t)(tok + r) * NPROJ + qcol + 8 * ch); } }
; #pragma unroll
;     ...
; #pragma unroll
;             for (int it = 0; it < 4; ++it) { const int item = tl + 512 * it, r = item >> 4, ch = item & 15; *(LAS u32x4*)(img + offb(r, ch)) = t[which][it]; } }
;         if (ci < 7) { const int cn = dir ? 6 - ci : ci + 1; const int tokn = tok0 + cn * 128;
; #pragma unroll
;             for (int which = 1; which < 3; ++which) { const int cb = which == 1 ? kcol : vcolg;
; #pragma unroll
;                 for (int it = 0; it < 4; ++it) { const int item = tl + 512 * it, r = item >> 4, ch = item & 15; t[which][it] = *(const u32x4*)(proj + (size_t)(tokn + r) * NPROJ + cb + 8 * ch); } } }
;     ...
;             __syncthreads();
; #pragma unroll
;             for (int nt = 0; nt < 8; ++nt) { u32x2 v; v.x = cvt_pk_bf16(Cacc[nt][0], Cacc[nt][1]); v.y = cvt_pk_bf16(Cacc[nt][2], Cacc[nt][3]);
;                 { LAUNDER_X16 *(LAS u32x2*)(lds + IMG_C + CWA(nt)) = v; } }
;             { u32x2 v; v.x = cvt_pk_bf16(Cacc[8][0], Cacc[8][1]); v.y = cvt_pk_bf16(Cacc[8][2], Cacc[8][3]); *(LAS u32x2*)(lds + IMG_CX + 32 * (16 * w + fr) + 8 * fg) = v; }
.Lqpf_stub:
	s_cmpk_eq_i32 s87, 0xfa00
	s_cbranch_scc1 .Lqpf_skip_s
	s_add_i32 s32, s7, 0x80
	s_xor_b32 s89, s32, 0x380
	s_cmp_lg_u64 s[8:9], 0
	s_cselect_b32 s32, s32, s89
	s_add_i32 s32, s32, s79
	v_ashrrev_i32_e32 v194, 4, v161
	v_lshlrev_b32_e32 v198, 4, v161
	v_add_u32_e32 v194, s32, v194
	v_and_b32_e32 v198, 0xf0, v198
	v_ashrrev_i32_e32 v195, 31, v194
	v_mov_b32_e32 v199, 0
	v_lshlrev_b64 v[194:195], 13, v[194:195]
	v_lshl_add_u64 v[198:199], s[36:37], 0, v[198:199]
	v_mov_b32_e32 v242, 0x40000
	v_mov_b32_e32 v243, 0
	v_lshl_add_u64 v[194:195], v[198:199], 0, v[194:195]
	v_lshl_add_u64 v[198:199], v[194:195], 0, v[242:243]
	v_lshl_add_u64 v[244:245], v[198:199], 0, v[242:243]
	v_lshl_add_u64 v[154:155], v[244:245], 0, v[242:243]
	s_nop 0
	global_load_dwordx4 v[194:197], v[194:195], off
	s_nop 0
	global_load_dwordx4 v[198:201], v[198:199], off
	s_nop 0
	global_load_dwordx4 v[242:245], v[244:245], off
	s_nop 0
	global_load_dword v202, v[154:155], off offset:8
	s_nop 0
	global_load_dword v186, v[154:155], off offset:12
	s_nop 0
	global_load_dwordx2 v[154:155], v[154:155], off
.Lqpf_skip_s:
.LBB0_97:
	v_mov_b32_e32 v0, v179
	s_barrier
	v_cvt_pk_bf16_f32 v72, v32, v33
	v_cvt_pk_bf16_f32 v73, v34, v35
	s_add_i32 s86, s86, -1
	v_add_u32_e32 v0, v180, v0
	ds_write_b64 v0, v[72:73]
	v_mov_b32_e32 v0, v179
	v_cvt_pk_bf16_f32 v72, v28, v29
	v_cvt_pk_bf16_f32 v73, v30, v31
	s_add_i32 s83, s83, 1
	v_xad_u32 v0, v0, 32, v180
	ds_write_b64 v0, v[72:73]
	v_mov_b32_e32 v0, v179
	v_cvt_pk_bf16_f32 v72, v24, v25
	v_cvt_pk_bf16_f32 v73, v26, v27
	s_addk_i32 s87, 0x600
	v_xad_u32 v0, v0, 64, v180
	ds_write_b64 v0, v[72:73]
	v_mov_b32_e32 v0, v179
	v_cvt_pk_bf16_f32 v72, v20, v21
	v_cvt_pk_bf16_f32 v73, v22, v23
	s_add_i32 s88, s88, 8
	v_xad_u32 v0, v0, s33, v180
	ds_write_b64 v0, v[72:73]
	v_mov_b32_e32 v0, v179
	v_cvt_pk_bf16_f32 v72, v16, v17
	v_cvt_pk_bf16_f32 v73, v18, v19
	s_addk_i32 s7, 0x80
	v_xad_u32 v0, v0, s25, v180
	ds_write_b64 v0, v[72:73]
	v_mov_b32_e32 v0, v179
	v_cvt_pk_bf16_f32 v72, v12, v13
	v_cvt_pk_bf16_f32 v73, v14, v15
	s_cmp_lg_u32 s87, 0
	v_xad_u32 v0, v0, s31, v180
	ds_write_b64 v0, v[72:73]
	v_mov_b32_e32 v0, v179
	v_cvt_pk_bf16_f32 v72, v8, v9
	v_cvt_pk_bf16_f32 v73, v10, v11
	s_nop 0
	v_xad_u32 v0, v0, s27, v180
	ds_write_b64 v0, v[72:73]
	v_mov_b32_e32 v0, v179
	v_cvt_pk_bf16_f32 v72, v4, v5
	v_cvt_pk_bf16_f32 v73, v6, v7
	s_nop 0
	v_xad_u32 v0, v0, s97, v180
	ds_write_b64 v0, v[72:73]
	v_cvt_pk_bf16_f32 v72, v36, v37
	v_cvt_pk_bf16_f32 v73, v38, v39
	ds_write_b64 v181, v[72:73]
	s_cbranch_scc0 .LBB0_74
.LBB0_98:
	s_xor_b32 s15, s7, 0x380
	s_and_b64 s[16:17], s[8:9], exec
	s_cselect_b32 s89, s7, s15
	v_mov_b32_e32 v92, v161
	s_add_i32 s89, s89, s79
	s_waitcnt lgkmcnt(0)
	s_barrier
	s_cmpk_eq_i32 s87, 0xfa00
	v_lshlrev_b32_e32 v0, 3, v92
	v_ashrrev_i32_e32 v72, 4, v92
	v_and_b32_e32 v0, 0x78, v0
	v_lshlrev_b32_e32 v0, 1, v0
	v_add_u32_e32 v73, 0x200, v92
	v_ashrrev_i32_e32 v73, 4, v73
	v_add_u32_e32 v74, 0x400, v92
	v_ashrrev_i32_e32 v74, 4, v74
	v_add_u32_e32 v75, 0x600, v92
	v_ashrrev_i32_e32 v75, 4, v75
	v_lshlrev_b32_e32 v94, 2, v72
	v_and_b32_e32 v92, 15, v92
	v_and_b32_e32 v94, 12, v94
	v_bfe_u32 v95, v72, 2, 2
	v_bitop3_b32 v94, v94, v92, v95 bitop3:0x36
	v_lshlrev_b32_e32 v96, 2, v73
	v_lshlrev_b32_e32 v93, 8, v72
	v_lshlrev_b32_e32 v94, 4, v94
	v_and_b32_e32 v96, 12, v96
	v_bfe_u32 v97, v73, 2, 2
	v_add3_u32 v95, s85, v94, v93
	v_bitop3_b32 v96, v96, v92, v97 bitop3:0x36
	v_lshlrev_b32_e32 v98, 2, v74
	s_waitcnt vmcnt(0)
	ds_write_b128 v95, v[56:59]
	v_lshlrev_b32_e32 v95, 8, v73
	v_lshlrev_b32_e32 v96, 4, v96
	v_and_b32_e32 v98, 12, v98
	v_bfe_u32 v99, v74, 2, 2
	v_add3_u32 v97, s85, v96, v95
	v_bitop3_b32 v98, v98, v92, v99 bitop3:0x36
	v_lshlrev_b32_e32 v100, 2, v75
	s_waitcnt vmcnt(6)
	ds_write_b128 v97, v[60:63]
	v_lshlrev_b32_e32 v97, 8, v74
	v_lshlrev_b32_e32 v98, 4, v98
	v_and_b32_e32 v100, 12, v100
	v_bfe_u32 v101, v75, 2, 2
	v_add3_u32 v99, s85, v98, v97
	v_bitop3_b32 v92, v100, v92, v101 bitop3:0x36
	s_waitcnt vmcnt(5)
	ds_write_b128 v99, v[64:67]
	v_lshlrev_b32_e32 v99, 8, v75
	v_lshlrev_b32_e32 v92, 4, v92
	v_add3_u32 v100, s85, v92, v99
	v_add3_u32 v93, 0, v94, v93
	v_add3_u32 v94, 0, v96, v95
	v_add3_u32 v95, 0, v98, v97
	v_add3_u32 v92, 0, v92, v99
	s_waitcnt vmcnt(4)
	ds_write_b128 v100, v[68:71]
	ds_write_b128 v93, v[40:43] offset:32768
	ds_write_b128 v94, v[44:47] offset:32768
	ds_write_b128 v95, v[48:51] offset:32768
	ds_write_b128 v92, v[52:55] offset:32768
	s_waitcnt vmcnt(3)
	ds_write_b128 v93, v[194:197]
	s_waitcnt vmcnt(2)
	ds_write_b128 v94, v[198:201]
	s_waitcnt vmcnt(1)
	ds_write_b128 v95, v[242:245]
	s_waitcnt vmcnt(0)
	ds_write_b64 v92, v[154:155]
	ds_write_b32 v92, v202 offset:8
	ds_write_b32 v92, v186 offset:12
	s_cbranch_scc1 .LBB0_100
	s_and_b64 s[16:17], s[8:9], exec
	s_cselect_b32 s15, s83, s86
	s_lshl_b32 s15, s15, 7
	s_add_i32 s15, s15, s79
	v_add_u32_e32 v40, s15, v72
	v_add_u32_e32 v42, s15, v73
	v_add_u32_e32 v50, s15, v74
	v_add_u32_e32 v52, s15, v75
	v_lshl_add_u64 v[56:57], s[22:23], 0, v[0:1]
	v_ashrrev_i32_e32 v41, 31, v40
	v_ashrrev_i32_e32 v43, 31, v42
	v_ashrrev_i32_e32 v51, 31, v50
	v_ashrrev_i32_e32 v53, 31, v52
	s_mov_b32 s15, s39
	v_lshlrev_b64 v[58:59], 13, v[40:41]
	v_lshl_add_u64 v[48:49], v[56:57], 0, s[38:39]
	v_lshlrev_b64 v[60:61], 13, v[42:43]
	v_lshlrev_b64 v[64:65], 13, v[50:51]
	v_lshlrev_b64 v[66:67], 13, v[52:53]
	v_lshl_add_u64 v[68:69], v[56:57], 0, s[14:15]
	v_lshl_add_u64 v[40:41], v[48:49], 0, v[58:59]
	v_lshl_add_u64 v[44:45], v[48:49], 0, v[60:61]
	v_lshl_add_u64 v[50:51], v[48:49], 0, v[64:65]
	v_lshl_add_u64 v[52:53], v[48:49], 0, v[66:67]
	v_lshl_add_u64 v[56:57], v[68:69], 0, v[58:59]
	v_lshl_add_u64 v[60:61], v[68:69], 0, v[60:61]
	v_lshl_add_u64 v[64:65], v[68:69], 0, v[64:65]
	v_lshl_add_u64 v[68:69], v[68:69], 0, v[66:67]
	global_load_dwordx4 v[40:43], v[40:41], off
	s_nop 0
	global_load_dwordx4 v[44:47], v[44:45], off
	s_nop 0
	global_load_dwordx4 v[48:51], v[50:51], off
	s_nop 0
	global_load_dwordx4 v[52:55], v[52:53], off
	s_nop 0
	global_load_dwordx4 v[56:59], v[56:57], off
	s_nop 0
	global_load_dwordx4 v[60:63], v[60:61], off
	s_nop 0
	global_load_dwordx4 v[64:67], v[64:65], off
	s_nop 0
	global_load_dwordx4 v[68:71], v[68:69], off

; __device__ __forceinline__ unsigned cvt_pk_bf16(float lo, float hi) { unsigned r; asm volatile("v_cvt_pk_bf16_f32 %0, %1, %2" : "=v"(r) : "v"(lo), "v"(hi)); return r; }
; __device__ __forceinline__ float bf_lo(unsigned w) { return __uint_as_float(w << 16); }
; __device__ __forceinline__ float bf_hi(unsigned w) { return __uint_as_float(w & 0xffff0000u); }
; __device__ void mix_sweep(const Params& P, LAS unsigned char* lds, int tok0, int pos0, int seqlen, int hd, int dir, bool state_only, bool final_pass,
;                           f32x4 (&Cacc)[9], float& m_state, float& aseg_sum, float lgam) {
;     ...
;             if (!final_pass) {
; #pragma unroll
;                 for (int nt = 0; nt < 8; ++nt) { u32x2 v; v.x = cvt_pk_bf16(O[nt][0] * hs, O[nt][1] * hs); v.y = cvt_pk_bf16(O[nt][2] * hs, O[nt][3] * hs); *(u32x2*)(mrow + 16 * nt) = v; }
;             } else {
;                 float sum = 0.f;
;                 const bf16_t* grow = proj + (size_t)(tok + irow) * NPROJ + gcol + 4 * fg;
;                 u32x2 hbv[8], gvv[8];
; #pragma unroll
;                 for (int nt = 0; nt < 8; ++nt) { hbv[nt] = *(const u32x2*)(mrow + 16 * nt); gvv[nt] = *(const u32x2*)(grow + 16 * nt); }
;                 __builtin_amdgcn_sched_barrier(0);
; #pragma unroll
;                 for (int nt = 0; nt < 8; ++nt) { const u32x2 hb = hbv[nt];
;                     O[nt][0] = O[nt][0] * hs + bf_lo(hb.x); O[nt][1] = O[nt][1] * hs + bf_hi(hb.x); O[nt][2] = O[nt][2] * hs + bf_lo(hb.y); O[nt][3] = O[nt][3] * hs + bf_hi(hb.y);
;                     sum += O[nt][0] + O[nt][1] + O[nt][2] + O[nt][3]; }
;                 sum += __shfl_xor(sum, 16); sum += __shfl_xor(sum, 32);
;                 const float mu = sum * (1.0f / 128.0f); float sq = 0.f;
.LBB0_369:
	s_andn2_b64 vcc, exec, s[16:17]
	s_cbranch_vccnz .Lqpf_stub
	v_lshlrev_b64 v[74:75], 13, v[74:75]
	v_lshl_add_u64 v[74:75], v[152:153], 0, v[74:75]
	global_load_dwordx2 v[94:95], v[74:75], off offset:128
	global_load_dwordx2 v[84:85], v[74:75], off offset:160
	global_load_dwordx2 v[76:77], v[74:75], off offset:192
	global_load_dwordx2 v[74:75], v[74:75], off offset:224
	s_waitcnt vmcnt(4)
	v_mov_b64_e32 v[88:89], v[204:205]
	v_mov_b64_e32 v[92:93], v[206:207]
	v_mov_b64_e32 v[96:97], v[222:223]
	v_mov_b64_e32 v[98:99], v[224:225]
	v_mov_b64_e32 v[148:149], v[226:227]
	v_mov_b64_e32 v[146:147], v[228:229]
	v_mov_b64_e32 v[110:111], v[230:231]
	v_mov_b64_e32 v[104:105], v[232:233]
	v_mov_b64_e32 v[150:151], v[234:235]
	v_mov_b64_e32 v[156:157], v[236:237]
	v_mov_b64_e32 v[158:159], v[238:239]
	v_mov_b64_e32 v[170:171], v[240:241]
	s_nop 0
	v_mov_b32_e32 v100, v80
	v_mov_b32_e32 v101, v112
	s_waitcnt vmcnt(14)
	v_lshlrev_b32_e32 v103, 16, v92
	v_lshlrev_b32_e32 v102, 16, v88
	v_mov_b32_e32 v112, v81
	v_and_b32_e32 v81, 0xffff0000, v92
	v_and_b32_e32 v80, 0xffff0000, v88
	v_pk_fma_f32 v[144:145], v[100:101], v[0:1], v[102:103] op_sel_hi:[1,0,1]
	v_pk_fma_f32 v[142:143], v[112:113], v[0:1], v[80:81] op_sel_hi:[1,0,1]
	v_mov_b32_e32 v80, v82
	v_mov_b32_e32 v81, v114
	v_lshlrev_b32_e32 v101, 16, v93
	v_lshlrev_b32_e32 v100, 16, v89
	v_pk_fma_f32 v[140:141], v[80:81], v[0:1], v[100:101] op_sel_hi:[1,0,1]
	v_mov_b32_e32 v114, v83
	v_and_b32_e32 v81, 0xffff0000, v93
	v_and_b32_e32 v80, 0xffff0000, v89
	v_pk_fma_f32 v[114:115], v[114:115], v[0:1], v[80:81] op_sel_hi:[1,0,1]
	v_pk_add_f32 v[80:81], v[144:145], v[142:143]
	s_waitcnt vmcnt(12)
	v_lshlrev_b32_e32 v90, 16, v98
	v_pk_add_f32 v[80:81], v[140:141], v[80:81]
	v_and_b32_e32 v106, 0xffff0000, v98
	v_pk_add_f32 v[80:81], v[114:115], v[80:81]
	v_fmac_f32_e32 v90, v128, v0
	v_add_f32_e32 v80, 0, v80
	v_add_f32_e32 v86, v80, v81
	v_lshlrev_b32_e32 v80, 16, v96
	v_and_b32_e32 v81, 0xffff0000, v96
	v_pk_fma_f32 v[112:113], v[120:121], v[0:1], v[80:81] op_sel_hi:[1,0,1]
	v_and_b32_e32 v81, 0xffff0000, v97
	v_lshlrev_b32_e32 v80, 16, v97
	v_pk_fma_f32 v[108:109], v[122:123], v[0:1], v[80:81] op_sel_hi:[1,0,1]
	v_pk_add_f32 v[80:81], v[112:113], v[112:113] op_sel:[0,1] op_sel_hi:[1,0]
	v_fmac_f32_e32 v106, v129, v0
	v_pk_add_f32 v[80:81], v[108:109], v[80:81]
	s_waitcnt vmcnt(7)
	v_and_b32_e32 v107, 0xffff0000, v150
	v_and_b32_e32 v92, 0xffff0000, v151
	v_mov_b32_e32 v82, v130
	v_mov_b32_e32 v83, v136
	v_lshlrev_b32_e32 v89, 16, v150
	v_lshlrev_b32_e32 v88, 16, v99
	v_pk_add_f32 v[80:81], v[108:109], v[80:81] op_sel:[1,0] op_sel_hi:[0,1]
	v_pk_fma_f32 v[102:103], v[82:83], v[0:1], v[88:89] op_sel_hi:[1,0,1]
	v_pk_add_f32 v[100:101], v[90:91], v[106:107]
	v_pk_mov_b32 v[82:83], v[130:131], v[138:139] op_sel:[1,0]
	v_and_b32_e32 v88, 0xffff0000, v99
	v_lshlrev_b32_e32 v89, 16, v151
	v_mov_b32_e32 v81, v92
	v_pk_fma_f32 v[96:97], v[82:83], v[0:1], v[88:89] op_sel_hi:[1,0,1]
	v_pk_add_f32 v[92:93], v[86:87], v[80:81]
	v_pk_add_f32 v[80:81], v[102:103], v[100:101]
	s_waitcnt vmcnt(4)
	v_and_b32_e32 v91, 0xffff0000, v171
	v_pk_add_f32 v[80:81], v[96:97], v[80:81]
	v_mov_b32_e32 v120, v126
	v_pk_add_f32 v[82:83], v[92:93], v[80:81]
	v_lshlrev_b32_e32 v80, 16, v156
	v_and_b32_e32 v81, 0xffff0000, v156
	v_pk_fma_f32 v[86:87], v[132:133], v[0:1], v[80:81] op_sel_hi:[1,0,1]
	v_and_b32_e32 v81, 0xffff0000, v157
	v_lshlrev_b32_e32 v80, 16, v157
	v_pk_fma_f32 v[80:81], v[134:135], v[0:1], v[80:81] op_sel_hi:[1,0,1]
	v_pk_add_f32 v[88:89], v[86:87], v[86:87] op_sel:[0,1] op_sel_hi:[1,0]
	v_pk_add_f32 v[82:83], v[82:83], v[82:83] op_sel:[0,1] op_sel_hi:[1,0]
	v_pk_add_f32 v[88:89], v[80:81], v[88:89]
	v_mov_b32_e32 v121, v116
	v_pk_add_f32 v[88:89], v[80:81], v[88:89] op_sel:[1,0] op_sel_hi:[0,1]
	v_lshlrev_b32_e32 v117, 16, v170
	v_lshlrev_b32_e32 v116, 16, v159
	v_mov_b32_e32 v83, v78
	v_mov_b32_e32 v89, v91
	v_pk_fma_f32 v[120:121], v[120:121], v[0:1], v[116:117] op_sel_hi:[1,0,1]
	v_pk_mov_b32 v[116:117], v[126:127], v[118:119] op_sel:[1,0]
	v_pk_add_f32 v[126:127], v[82:83], v[88:89]
	v_and_b32_e32 v82, 64, v203
	v_xor_b32_e32 v78, 16, v203
	v_add_u32_e32 v91, 64, v82
	v_cmp_lt_i32_e32 vcc, v78, v91
	v_and_b32_e32 v83, 0xffff0000, v158
	v_lshlrev_b32_e32 v82, 16, v158
	v_cndmask_b32_e32 v78, v203, v78, vcc
	v_pk_fma_f32 v[82:83], v[124:125], v[0:1], v[82:83] op_sel_hi:[1,0,1]
	v_and_b32_e32 v99, 0xffff0000, v170
	v_lshlrev_b32_e32 v100, 2, v78
	v_mov_b32_e32 v78, v82
	v_mov_b32_e32 v98, v83
	v_and_b32_e32 v118, 0xffff0000, v159
	v_lshlrev_b32_e32 v119, 16, v171
	v_pk_add_f32 v[78:79], v[78:79], v[98:99]
	v_pk_fma_f32 v[122:123], v[116:117], v[0:1], v[118:119] op_sel_hi:[1,0,1]
	v_pk_add_f32 v[88:89], v[120:121], v[78:79]
	v_bfe_u32 v116, v161, 4, 2
	v_lshlrev_b32_e32 v116, 4, v116
	v_add_u32_e32 v116, 0x25a80, v116
	ds_read_b128 v[116:119], v116
	v_pk_add_f32 v[88:89], v[122:123], v[88:89]
	s_nop 0
	v_pk_add_f32 v[88:89], v[126:127], v[88:89]
	s_nop 0
	v_add_f32_e32 v0, v88, v89
	ds_bpermute_b32 v78, v100, v0
	v_xor_b32_e32 v88, 32, v203
	v_cmp_lt_i32_e32 vcc, v88, v91
	s_waitcnt lgkmcnt(0)
	v_add_f32_e32 v0, v0, v78
	v_cndmask_b32_e32 v88, v203, v88, vcc
	v_lshlrev_b32_e32 v107, 2, v88
	ds_bpermute_b32 v78, v107, v0
	s_waitcnt lgkmcnt(0)
; __device__ void mix_sweep(const Params& P, LAS unsigned char* lds, int tok0, int pos0, int seqlen, int hd, int dir, bool state_only, bool final_pass,
;                           f32x4 (&Cacc)[9], float& m_state, float& aseg_sum, float lgam) {
;     ...
;             for (int it = 0; it < 4; ++it) { const int item = tl + 512 * it, r = item >> 4, ch = item & 15; t[0][it] = *(const u32x4*)(proj + (size_t)(tok + r) * NPROJ + qcol + 8 * ch); } }
;     ...
;                 const float mu = sum * (1.0f / 128.0f); float sq = 0.f;
; #pragma unroll
;                 for (int nt = 0; nt < 8; ++nt)
; #pragma unroll
;                     for (int e = 0; e < 4; ++e) { const float d = O[nt][e] - mu; sq += d * d; }
;                 sq += __shfl_xor(sq, 16); sq += __shfl_xor(sq, 32);
;                 const float rs = rsqrtf(sq * (1.0f / 128.0f) + 1e-5f);
; #pragma unroll
	v_add_f32_e32 v78, v0, v78
	v_fmamk_f32 v125, v78, 0xbc000000, v142
	v_fmamk_f32 v124, v78, 0xbc000000, v144
	v_mul_f32_e32 v88, v125, v125
	v_fmac_f32_e32 v88, v124, v124
	v_fmamk_f32 v126, v78, 0xbc000000, v140
	v_fmac_f32_e32 v88, v126, v126
	v_fmamk_f32 v114, v78, 0xbc000000, v114
	v_fmac_f32_e32 v88, v114, v114
	v_fmac_f32_e32 v145, 0xbc000000, v78
	v_fmac_f32_e32 v88, v145, v145
	v_fmac_f32_e32 v143, 0xbc000000, v78
	v_fmac_f32_e32 v88, v143, v143
	v_fmac_f32_e32 v141, 0xbc000000, v78
	v_fmac_f32_e32 v88, v141, v141
	v_fmac_f32_e32 v115, 0xbc000000, v78
	v_fmac_f32_e32 v88, v115, v115
	v_fmamk_f32 v112, v78, 0xbc000000, v112
	v_fmac_f32_e32 v88, v112, v112
	v_fmac_f32_e32 v113, 0xbc000000, v78
	v_fmac_f32_e32 v88, v113, v113
	v_fmamk_f32 v108, v78, 0xbc000000, v108
	v_fmac_f32_e32 v88, v108, v108
	v_fmac_f32_e32 v109, 0xbc000000, v78
	v_fmac_f32_e32 v88, v109, v109
	v_fmac_f32_e32 v90, 0xbc000000, v78
	v_fmac_f32_e32 v88, v90, v90
	v_fmac_f32_e32 v106, 0xbc000000, v78
	v_fmac_f32_e32 v88, v106, v106
	v_fmamk_f32 v92, v78, 0xbc000000, v102
	v_fmac_f32_e32 v88, v92, v92
	v_fmamk_f32 v91, v78, 0xbc000000, v96
	v_fmac_f32_e32 v88, v91, v91
	v_fmac_f32_e32 v103, 0xbc000000, v78
	v_fmac_f32_e32 v88, v103, v103
	v_fmac_f32_e32 v101, 0xbc000000, v78
	v_fmac_f32_e32 v88, v101, v101
	v_fmac_f32_e32 v97, 0xbc000000, v78
	v_fmac_f32_e32 v88, v97, v97
	v_fmac_f32_e32 v93, 0xbc000000, v78
	v_fmac_f32_e32 v88, v93, v93
	v_fmamk_f32 v86, v78, 0xbc000000, v86
	v_fmac_f32_e32 v88, v86, v86
	v_fmac_f32_e32 v87, 0xbc000000, v78
	v_mul_f32_e32 v0, 0x3c000000, v78
	v_fmac_f32_e32 v88, v87, v87
	v_fmamk_f32 v80, v78, 0xbc000000, v80
	v_fmac_f32_e32 v88, v80, v80
	v_fmac_f32_e32 v81, 0xbc000000, v78
	v_pk_add_f32 v[98:99], v[82:83], v[0:1] op_sel_hi:[1,0] neg_lo:[0,1] neg_hi:[0,1]
	v_fmac_f32_e32 v88, v81, v81
	v_pk_mul_f32 v[82:83], v[98:99], v[98:99]
	s_nop 0
	v_add_f32_e32 v78, v82, v88
	v_add_f32_e32 v78, v83, v78
	v_mov_b32_e32 v82, v122
	v_mov_b32_e32 v83, v120
	v_pk_add_f32 v[88:89], v[82:83], v[0:1] op_sel_hi:[1,0] neg_lo:[0,1] neg_hi:[0,1]
	v_mov_b32_e32 v120, v79
	v_pk_mul_f32 v[82:83], v[88:89], v[88:89]
	v_mov_b32_e32 v122, v127
	v_add_f32_e32 v78, v83, v78
	v_add_f32_e32 v96, v82, v78
	v_pk_add_f32 v[82:83], v[120:121], v[0:1] op_sel_hi:[1,0] neg_lo:[0,1] neg_hi:[0,1]
	s_nop 0
	v_pk_mul_f32 v[78:79], v[82:83], v[82:83]
	s_nop 0
	v_add_f32_e32 v79, v79, v96
	v_add_f32_e32 v96, v78, v79
	v_pk_add_f32 v[78:79], v[122:123], v[0:1] op_sel_hi:[1,0] neg_lo:[0,1] neg_hi:[0,1]
	v_and_b32_e32 v122, 0xffff0000, v149
	v_pk_mul_f32 v[120:121], v[78:79], v[78:79]
	s_nop 0
	v_add_f32_e32 v0, v121, v96
	v_add_f32_e32 v0, v120, v0
	ds_bpermute_b32 v96, v100, v0
	v_and_b32_e32 v120, 0xffff0000, v148
	v_lshlrev_b32_e32 v121, 16, v149
	s_waitcnt lgkmcnt(0)
	v_add_f32_e32 v0, v0, v96
	ds_bpermute_b32 v96, v107, v0
	s_waitcnt lgkmcnt(0)
	v_add_f32_e32 v0, v0, v96
	v_mov_b32_e32 v96, 0x3727c5ac
	v_fmamk_f32 v0, v0, 0x3c000000, v96
	v_mul_f32_e32 v96, 0x4b800000, v0
	v_cmp_gt_f32_e32 vcc, s30, v0
	s_nop 1
	v_cndmask_b32_e32 v0, v0, v96, vcc
	v_lshlrev_b32_e32 v96, 16, v148
	v_mul_f32_e32 v100, 0xbfb8aa3b, v96
	v_rsq_f32_e32 v0, v0
	v_exp_f32_e32 v100, v100
	v_mul_f32_e32 v102, 0x45800000, v0
	v_add_f32_e32 v100, 1.0, v100
	v_cndmask_b32_e32 v0, v0, v102, vcc
	v_mul_f32_e32 v114, v114, v0
	s_waitcnt vmcnt(0) lgkmcnt(0)
	s_cmpk_eq_i32 s87, 0xfa00
	s_cbranch_scc1 .Lqpf_skip_m
	s_add_i32 s32, s7, 0x80
	s_xor_b32 s89, s32, 0x380
	s_cmp_lg_u64 s[8:9], 0
	s_cselect_b32 s32, s32, s89
	s_add_i32 s32, s32, s79
	v_ashrrev_i32_e32 v194, 4, v161
	v_lshlrev_b32_e32 v198, 4, v161
	v_add_u32_e32 v194, s32, v194
	v_and_b32_e32 v198, 0xf0, v198
	v_ashrrev_i32_e32 v195, 31, v194
	v_mov_b32_e32 v199, 0
	v_lshlrev_b64 v[194:195], 13, v[194:195]
	v_lshl_add_u64 v[198:199], s[36:37], 0, v[198:199]
	v_mov_b32_e32 v242, 0x40000
	v_mov_b32_e32 v243, 0
	v_lshl_add_u64 v[194:195], v[198:199], 0, v[194:195]
	v_lshl_add_u64 v[198:199], v[194:195], 0, v[242:243]
	v_lshl_add_u64 v[244:245], v[198:199], 0, v[242:243]
	v_lshl_add_u64 v[154:155], v[244:245], 0, v[242:243]
	s_nop 0
	global_load_dwordx4 v[194:197], v[194:195], off
	s_nop 0
	global_load_dwordx4 v[198:201], v[198:199], off
	s_nop 0
	global_load_dwordx4 v[242:245], v[244:245], off
	s_nop 0
	global_load_dword v202, v[154:155], off offset:8
	s_nop 0
	global_load_dword v186, v[154:155], off offset:12
	s_nop 0
	global_load_dwordx2 v[154:155], v[154:155], off
; __device__ __forceinline__ unsigned cvt_pk_bf16(float lo, float hi) { unsigned r; asm volatile("v_cvt_pk_bf16_f32 %0, %1, %2" : "=v"(r) : "v"(lo), "v"(hi)); return r; }
; __device__ __forceinline__ float bf_lo(unsigned w) { return __uint_as_float(w << 16); }
; __device__ __forceinline__ float bf_hi(unsigned w) { return __uint_as_float(w & 0xffff0000u); }
; __device__ __forceinline__ float sigmoidf_(float x) { return 1.0f / (1.0f + __expf(-x)); }
; __device__ void mix_sweep(const Params& P, LAS unsigned char* lds, int tok0, int pos0, int seqlen, int hd, int dir, bool state_only, bool final_pass,
;                           f32x4 (&Cacc)[9], float& m_state, float& aseg_sum, float lgam) {
;     ...
;                 for (int nt = 0; nt < 8; ++nt) { const u32x2 gv = gvv[nt]; const f32x4 gw = *(const f32x4*)(gnw + 16 * nt + 4 * fg);
;                     float gt[4] = {bf_lo(gv.x), bf_hi(gv.x), bf_lo(gv.y), bf_hi(gv.y)}; float y[4];
; #pragma unroll
;                     for (int e = 0; e < 4; ++e) { const float sg = sigmoidf_(gt[e]); const float gate = is_m ? sg : gt[e] * sg; y[e] = (O[nt][e] - mu) * rs * gw[e] * gate; }
;                     u32x2 v; v.x = cvt_pk_bf16(y[0], y[1]); v.y = cvt_pk_bf16(y[2], y[3]); *(u32x2*)(mrow + 16 * nt) = v; }
.Lqpf_skip_m:
	v_mul_f32_e32 v114, v119, v114
	v_mul_f32_e32 v112, v112, v0
	v_mul_f32_e32 v107, 0xbfb8aa3b, v120
	v_exp_f32_e32 v107, v107
	v_rcp_f32_e32 v102, v100
	s_nop 0
	v_fma_f32 v127, -v100, v102, 1.0
	v_fma_f32 v100, v127, v102, v102
	v_mul_f32_e32 v96, v100, v96
	v_cndmask_b32_e64 v96, v96, v100, s[40:41]
	v_add_f32_e32 v100, 1.0, v107
	v_div_scale_f32 v102, s[16:17], v100, v100, 1.0
	v_rcp_f32_e32 v107, v102
	v_mul_f32_e32 v123, v124, v0
	v_mul_f32_e32 v116, v116, v123
	v_mul_f32_e32 v96, v96, v116
	v_fma_f32 v116, -v102, v107, 1.0
	v_fmac_f32_e32 v107, v116, v107
	v_div_scale_f32 v116, vcc, 1.0, v100, 1.0
	v_mul_f32_e32 v123, v116, v107
	v_fma_f32 v124, -v102, v123, v116
	v_fmac_f32_e32 v123, v124, v107
	v_fma_f32 v102, -v102, v123, v116
	v_div_fmas_f32 v102, v102, v107, v123
	v_mul_f32_e32 v107, 0xbfb8aa3b, v121
	v_exp_f32_e32 v107, v107
	v_div_fixup_f32 v100, v102, v100, 1.0
	v_mul_f32_e32 v102, v100, v120
	v_cndmask_b32_e64 v100, v102, v100, s[40:41]
	v_add_f32_e32 v102, 1.0, v107
	v_mul_f32_e32 v120, v125, v0
	v_mul_f32_e32 v117, v117, v120
	v_mul_f32_e32 v100, v100, v117
	v_mul_f32_e32 v116, 0xbfb8aa3b, v122
	v_exp_f32_e32 v116, v116
	v_rcp_f32_e32 v107, v102
	s_nop 0
	v_fma_f32 v123, -v102, v107, 1.0
	v_fma_f32 v102, v123, v107, v107
	v_mul_f32_e32 v107, v102, v121
	v_cndmask_b32_e64 v102, v107, v102, s[40:41]
	v_add_f32_e32 v107, 1.0, v116
	v_mul_f32_e32 v120, v126, v0
	v_mul_f32_e32 v118, v118, v120
	v_mul_f32_e32 v102, v102, v118
	v_rcp_f32_e32 v116, v107
	s_nop 0
	v_fma_f32 v121, -v107, v116, 1.0
	v_fma_f32 v107, v121, v116, v116
	v_mul_f32_e32 v116, v107, v122
	v_cndmask_b32_e64 v107, v116, v107, s[40:41]
	v_mul_f32_e32 v107, v107, v114
	v_cvt_pk_bf16_f32 v116, v96, v100
	v_cvt_pk_bf16_f32 v117, v102, v107
	global_store_dwordx2 v[72:73], v[116:117], off
	v_bfe_u32 v116, v161, 4, 2
	v_lshlrev_b32_e32 v116, 4, v116
	v_add_u32_e32 v116, 0x25a80, v116
	ds_read_b128 v[116:119], v116 offset:64
	v_lshlrev_b32_e32 v96, 16, v146
	v_mul_f32_e32 v100, 0xbfb8aa3b, v96
	v_exp_f32_e32 v100, v100
	v_and_b32_e32 v114, 0xffff0000, v146
	v_lshlrev_b32_e32 v120, 16, v147
	v_and_b32_e32 v121, 0xffff0000, v147
	v_add_f32_e32 v100, 1.0, v100
	v_mul_f32_e32 v108, v108, v0
	v_mul_f32_e32 v90, v90, v0
	v_mul_f32_e32 v106, v106, v0
	v_mul_f32_e32 v107, 0xbfb8aa3b, v114
	v_exp_f32_e32 v107, v107
	v_rcp_f32_e32 v102, v100
	s_nop 0
	v_fma_f32 v123, -v100, v102, 1.0
	v_fma_f32 v100, v123, v102, v102
	v_mul_f32_e32 v96, v100, v96
	v_cndmask_b32_e64 v96, v96, v100, s[40:41]
	v_add_f32_e32 v100, 1.0, v107
	v_mul_f32_e32 v122, v145, v0
	v_mul_f32_e32 v92, v92, v0
	v_mul_f32_e32 v91, v91, v0
	v_mul_f32_e32 v101, v101, v0
	v_mul_f32_e32 v97, v97, v0
	v_mul_f32_e32 v93, v93, v0
	v_mul_f32_e32 v86, v86, v0
	v_mul_f32_e32 v87, v87, v0
	v_mul_f32_e32 v80, v80, v0
	v_mul_f32_e32 v81, v81, v0
	v_mul_f32_e32 v89, v89, v0
	v_mul_f32_e32 v83, v83, v0
	v_mul_f32_e32 v82, v82, v0
	v_mul_f32_e32 v79, v79, v0
	s_waitcnt lgkmcnt(0)
	v_mul_f32_e32 v116, v116, v122
	v_mul_f32_e32 v96, v96, v116
	v_mul_f32_e32 v107, 0xbfb8aa3b, v120
	v_exp_f32_e32 v107, v107
	v_rcp_f32_e32 v102, v100
	s_nop 0
	v_fma_f32 v123, -v100, v102, 1.0
	v_fma_f32 v100, v123, v102, v102
	v_mul_f32_e32 v102, v100, v114
	v_cndmask_b32_e64 v100, v102, v100, s[40:41]
	v_add_f32_e32 v102, 1.0, v107
	v_mul_f32_e32 v116, v143, v0
	v_mul_f32_e32 v116, v117, v116
	v_mul_f32_e32 v100, v100, v116
	v_mul_f32_e32 v114, 0xbfb8aa3b, v121
	v_exp_f32_e32 v114, v114
	v_rcp_f32_e32 v107, v102
	s_nop 0
	v_fma_f32 v122, -v102, v107, 1.0
	v_fma_f32 v102, v122, v107, v107
	v_mul_f32_e32 v107, v102, v120
	v_cndmask_b32_e64 v102, v107, v102, s[40:41]
	v_add_f32_e32 v107, 1.0, v114
	v_mul_f32_e32 v117, v141, v0
	v_mul_f32_e32 v117, v118, v117
	v_mul_f32_e32 v102, v102, v117
	v_rcp_f32_e32 v114, v107
	s_nop 0
	v_fma_f32 v120, -v107, v114, 1.0
	v_fma_f32 v107, v120, v114, v114
	v_mul_f32_e32 v114, v107, v121
	v_cndmask_b32_e64 v107, v114, v107, s[40:41]
	v_mul_f32_e32 v114, v115, v0
	v_mul_f32_e32 v114, v119, v114
	v_mul_f32_e32 v107, v107, v114
	v_cvt_pk_bf16_f32 v114, v96, v100
	v_cvt_pk_bf16_f32 v115, v102, v107
	global_store_dwordx2 v[72:73], v[114:115], off offset:32
	v_bfe_u32 v114, v161, 4, 2
	v_lshlrev_b32_e32 v114, 4, v114
	v_add_u32_e32 v114, 0x25a80, v114
	ds_read_b128 v[114:117], v114 offset:128
	v_lshlrev_b32_e32 v96, 16, v110
	v_mul_f32_e32 v100, 0xbfb8aa3b, v96
	v_exp_f32_e32 v100, v100
	v_and_b32_e32 v110, 0xffff0000, v110
	v_lshlrev_b32_e32 v118, 16, v111
	v_and_b32_e32 v111, 0xffff0000, v111
	v_add_f32_e32 v100, 1.0, v100
	s_waitcnt lgkmcnt(0)
	v_mul_f32_e32 v112, v114, v112
	v_mul_f32_e32 v107, 0xbfb8aa3b, v110
	v_exp_f32_e32 v107, v107
	v_rcp_f32_e32 v102, v100
	s_nop 0
	v_fma_f32 v120, -v100, v102, 1.0
	v_fma_f32 v100, v120, v102, v102
	v_mul_f32_e32 v96, v100, v96
	v_cndmask_b32_e64 v96, v96, v100, s[40:41]
	v_add_f32_e32 v100, 1.0, v107
	v_mul_f32_e32 v96, v96, v112
	v_mul_f32_e32 v108, v116, v108
	v_mul_f32_e32 v107, 0xbfb8aa3b, v118
	v_exp_f32_e32 v107, v107
	v_rcp_f32_e32 v102, v100
	s_nop 0
	v_fma_f32 v114, -v100, v102, 1.0
	v_fma_f32 v100, v114, v102, v102
	v_mul_f32_e32 v102, v100, v110
	v_cndmask_b32_e64 v100, v102, v100, s[40:41]
	v_add_f32_e32 v102, 1.0, v107
	v_mul_f32_e32 v112, v113, v0
	v_mul_f32_e32 v112, v115, v112
	v_mul_f32_e32 v100, v100, v112
	v_mul_f32_e32 v110, 0xbfb8aa3b, v111
	v_exp_f32_e32 v110, v110
	v_rcp_f32_e32 v107, v102
	s_nop 0
	v_fma_f32 v114, -v102, v107, 1.0
	v_fma_f32 v102, v114, v107, v107
	v_mul_f32_e32 v107, v102, v118
	v_cndmask_b32_e64 v102, v107, v102, s[40:41]
	v_add_f32_e32 v107, 1.0, v110
	v_mul_f32_e32 v102, v102, v108
	v_rcp_f32_e32 v113, v107
	s_nop 0
	v_fma_f32 v114, -v107, v113, 1.0
	v_fma_f32 v107, v114, v113, v113
	v_mul_f32_e32 v108, v107, v111
	v_cndmask_b32_e64 v107, v108, v107, s[40:41]
	v_mul_f32_e32 v108, v109, v0
	v_mul_f32_e32 v108, v117, v108
	v_mul_f32_e32 v107, v107, v108
	v_cvt_pk_bf16_f32 v108, v96, v100
	v_cvt_pk_bf16_f32 v109, v102, v107
	global_store_dwordx2 v[72:73], v[108:109], off offset:64
	v_bfe_u32 v108, v161, 4, 2
	v_lshlrev_b32_e32 v108, 4, v108
	v_add_u32_e32 v108, 0x25a80, v108
	ds_read_b128 v[108:111], v108 offset:192
	v_lshlrev_b32_e32 v96, 16, v104
	v_mul_f32_e32 v100, 0xbfb8aa3b, v96
	v_exp_f32_e32 v100, v100
	v_and_b32_e32 v104, 0xffff0000, v104
	v_lshlrev_b32_e32 v112, 16, v105
	v_and_b32_e32 v105, 0xffff0000, v105
	v_add_f32_e32 v100, 1.0, v100
	s_waitcnt lgkmcnt(0)
; __device__ __forceinline__ unsigned cvt_pk_bf16(float lo, float hi) { unsigned r; asm volatile("v_cvt_pk_bf16_f32 %0, %1, %2" : "=v"(r) : "v"(lo), "v"(hi)); return r; }
; __device__ __forceinline__ float bf_lo(unsigned w) { return __uint_as_float(w << 16); }
; __device__ __forceinline__ float bf_hi(unsigned w) { return __uint_as_float(w & 0xffff0000u); }
; __device__ __forceinline__ float sigmoidf_(float x) { return 1.0f / (1.0f + __expf(-x)); }
; __device__ void mix_sweep(const Params& P, LAS unsigned char* lds, int tok0, int pos0, int seqlen, int hd, int dir, bool state_only, bool final_pass,
;                           f32x4 (&Cacc)[9], float& m_state, float& aseg_sum, float lgam) {
;     ...
;                 for (int nt = 0; nt < 8; ++nt) { const u32x2 gv = gvv[nt]; const f32x4 gw = *(const f32x4*)(gnw + 16 * nt + 4 * fg);
;                     float gt[4] = {bf_lo(gv.x), bf_hi(gv.x), bf_lo(gv.y), bf_hi(gv.y)}; float y[4];
; #pragma unroll
;                     for (int e = 0; e < 4; ++e) { const float sg = sigmoidf_(gt[e]); const float gate = is_m ? sg : gt[e] * sg; y[e] = (O[nt][e] - mu) * rs * gw[e] * gate; }
;                     u32x2 v; v.x = cvt_pk_bf16(y[0], y[1]); v.y = cvt_pk_bf16(y[2], y[3]); *(u32x2*)(mrow + 16 * nt) = v; }
	v_mul_f32_e32 v90, v108, v90
	v_mul_f32_e32 v107, 0xbfb8aa3b, v104
	v_exp_f32_e32 v107, v107
	v_rcp_f32_e32 v102, v100
	s_nop 0
	v_fma_f32 v114, -v100, v102, 1.0
	v_fma_f32 v100, v114, v102, v102
	v_mul_f32_e32 v96, v100, v96
	v_cndmask_b32_e64 v96, v96, v100, s[40:41]
	v_add_f32_e32 v100, 1.0, v107
	v_mul_f32_e32 v90, v96, v90
	v_mul_f32_e32 v106, v109, v106
	v_mul_f32_e32 v92, v110, v92
	v_mul_f32_e32 v102, 0xbfb8aa3b, v112
	v_exp_f32_e32 v102, v102
	v_rcp_f32_e32 v108, v100
	s_nop 0
	v_fma_f32 v113, -v100, v108, 1.0
	v_fma_f32 v96, v113, v108, v108
	v_mul_f32_e32 v100, v96, v104
	v_cndmask_b32_e64 v96, v100, v96, s[40:41]
	v_add_f32_e32 v100, 1.0, v102
	v_mul_f32_e32 v96, v96, v106
	v_mul_f32_e32 v91, v111, v91
	v_cvt_pk_bf16_f32 v90, v90, v96
	v_mul_f32_e32 v104, 0xbfb8aa3b, v105
	v_exp_f32_e32 v104, v104
	v_rcp_f32_e32 v102, v100
	s_nop 0
	v_fma_f32 v107, -v100, v102, 1.0
	v_fma_f32 v100, v107, v102, v102
	v_mul_f32_e32 v102, v100, v112
	v_cndmask_b32_e64 v100, v102, v100, s[40:41]
	v_add_f32_e32 v102, 1.0, v104
	v_mul_f32_e32 v92, v100, v92
	v_rcp_f32_e32 v107, v102
	s_nop 0
	v_fma_f32 v108, -v102, v107, 1.0
	v_fma_f32 v100, v108, v107, v107
	v_mul_f32_e32 v102, v100, v105
	v_cndmask_b32_e64 v100, v102, v100, s[40:41]
	v_mul_f32_e32 v91, v100, v91
	v_cvt_pk_bf16_f32 v91, v92, v91
	global_store_dwordx2 v[72:73], v[90:91], off offset:96
	v_bfe_u32 v104, v161, 4, 2
	v_lshlrev_b32_e32 v104, 4, v104
	v_add_u32_e32 v104, 0x25a80, v104
	ds_read_b128 v[104:107], v104 offset:256
	v_lshlrev_b32_e32 v90, 16, v94
	v_mul_f32_e32 v91, 0xbfb8aa3b, v90
	v_exp_f32_e32 v91, v91
	v_and_b32_e32 v94, 0xffff0000, v94
	v_lshlrev_b32_e32 v100, 16, v95
	v_and_b32_e32 v95, 0xffff0000, v95
	v_add_f32_e32 v91, 1.0, v91
	s_waitcnt lgkmcnt(0)
	v_mul_f32_e32 v101, v105, v101
	v_mul_f32_e32 v96, 0xbfb8aa3b, v94
	v_exp_f32_e32 v96, v96
	v_rcp_f32_e32 v92, v91
	s_nop 0
	v_fma_f32 v108, -v91, v92, 1.0
	v_fma_f32 v91, v108, v92, v92
	v_mul_f32_e32 v90, v91, v90
	v_cndmask_b32_e64 v90, v90, v91, s[40:41]
	v_add_f32_e32 v91, 1.0, v96
	v_div_scale_f32 v92, s[16:17], v91, v91, 1.0
	v_rcp_f32_e32 v96, v92
	v_mul_f32_e32 v102, v103, v0
	v_mul_f32_e32 v102, v104, v102
	v_mul_f32_e32 v90, v90, v102
	v_fma_f32 v102, -v92, v96, 1.0
	v_fmac_f32_e32 v96, v102, v96
	v_div_scale_f32 v102, vcc, 1.0, v91, 1.0
	v_mul_f32_e32 v103, v102, v96
	v_fma_f32 v104, -v92, v103, v102
	v_fmac_f32_e32 v103, v104, v96
	v_fma_f32 v92, -v92, v103, v102
	v_div_fmas_f32 v92, v92, v96, v103
	v_mul_f32_e32 v96, 0xbfb8aa3b, v100
	v_exp_f32_e32 v96, v96
	v_div_fixup_f32 v91, v92, v91, 1.0
	v_mul_f32_e32 v92, v91, v94
	v_cndmask_b32_e64 v91, v92, v91, s[40:41]
	v_add_f32_e32 v92, 1.0, v96
	v_mul_f32_e32 v91, v91, v101
	v_mul_f32_e32 v97, v106, v97
	v_mul_f32_e32 v93, v107, v93
	v_mul_f32_e32 v96, 0xbfb8aa3b, v95
	v_exp_f32_e32 v96, v96
	v_rcp_f32_e32 v94, v92
	s_nop 0
	v_fma_f32 v102, -v92, v94, 1.0
	v_fma_f32 v92, v102, v94, v94
	v_mul_f32_e32 v94, v92, v100
	v_cndmask_b32_e64 v92, v94, v92, s[40:41]
	v_add_f32_e32 v94, 1.0, v96
	v_mul_f32_e32 v92, v92, v97
	v_cvt_pk_bf16_f32 v90, v90, v91
	v_rcp_f32_e32 v96, v94
	s_nop 0
	v_fma_f32 v101, -v94, v96, 1.0
	v_fma_f32 v94, v101, v96, v96
	v_mul_f32_e32 v95, v94, v95
	v_cndmask_b32_e64 v94, v95, v94, s[40:41]
	v_mul_f32_e32 v93, v94, v93
	v_cvt_pk_bf16_f32 v91, v92, v93
	global_store_dwordx2 v[72:73], v[90:91], off offset:128
	v_bfe_u32 v90, v161, 4, 2
	v_lshlrev_b32_e32 v90, 4, v90
	v_add_u32_e32 v90, 0x25a80, v90
	ds_read_b128 v[90:93], v90 offset:320
	v_lshlrev_b32_e32 v94, 16, v84
	v_mul_f32_e32 v95, 0xbfb8aa3b, v94
	v_exp_f32_e32 v95, v95
	v_and_b32_e32 v84, 0xffff0000, v84
	v_lshlrev_b32_e32 v100, 16, v85
	v_and_b32_e32 v85, 0xffff0000, v85
	v_add_f32_e32 v95, 1.0, v95
	s_waitcnt lgkmcnt(0)
; __device__ __forceinline__ unsigned cvt_pk_bf16(float lo, float hi) { unsigned r; asm volatile("v_cvt_pk_bf16_f32 %0, %1, %2" : "=v"(r) : "v"(lo), "v"(hi)); return r; }
; __device__ __forceinline__ float bf_lo(unsigned w) { return __uint_as_float(w << 16); }
; __device__ __forceinline__ float bf_hi(unsigned w) { return __uint_as_float(w & 0xffff0000u); }
; __device__ __forceinline__ float sigmoidf_(float x) { return 1.0f / (1.0f + __expf(-x)); }
; __device__ void mix_sweep(const Params& P, LAS unsigned char* lds, int tok0, int pos0, int seqlen, int hd, int dir, bool state_only, bool final_pass,
;                           f32x4 (&Cacc)[9], float& m_state, float& aseg_sum, float lgam) {
;     ...
;                 for (int nt = 0; nt < 8; ++nt) { const u32x2 gv = gvv[nt]; const f32x4 gw = *(const f32x4*)(gnw + 16 * nt + 4 * fg);
;                     float gt[4] = {bf_lo(gv.x), bf_hi(gv.x), bf_lo(gv.y), bf_hi(gv.y)}; float y[4];
; #pragma unroll
;                     for (int e = 0; e < 4; ++e) { const float sg = sigmoidf_(gt[e]); const float gate = is_m ? sg : gt[e] * sg; y[e] = (O[nt][e] - mu) * rs * gw[e] * gate; }
;                     u32x2 v; v.x = cvt_pk_bf16(y[0], y[1]); v.y = cvt_pk_bf16(y[2], y[3]); *(u32x2*)(mrow + 16 * nt) = v; }
	v_mul_f32_e32 v86, v90, v86
	v_mul_f32_e32 v97, 0xbfb8aa3b, v84
	v_exp_f32_e32 v97, v97
	v_rcp_f32_e32 v96, v95
	s_nop 0
	v_fma_f32 v102, -v95, v96, 1.0
	v_fma_f32 v95, v102, v96, v96
	v_mul_f32_e32 v94, v95, v94
	v_cndmask_b32_e64 v94, v94, v95, s[40:41]
	v_add_f32_e32 v95, 1.0, v97
	v_mul_f32_e32 v86, v94, v86
	v_mul_f32_e32 v87, v91, v87
	v_mul_f32_e32 v80, v92, v80
	v_mul_f32_e32 v94, 0xbfb8aa3b, v100
	v_exp_f32_e32 v94, v94
	v_rcp_f32_e32 v101, v95
	s_nop 0
	v_fma_f32 v97, -v95, v101, 1.0
	v_fma_f32 v90, v97, v101, v101
	v_mul_f32_e32 v84, v90, v84
	v_cndmask_b32_e64 v84, v84, v90, s[40:41]
	v_add_f32_e32 v90, 1.0, v94
	v_mul_f32_e32 v84, v84, v87
	v_mul_f32_e32 v81, v93, v81
	v_mul_f32_e32 v91, 0xbfb8aa3b, v85
	v_exp_f32_e32 v91, v91
	v_rcp_f32_e32 v96, v90
	s_nop 0
	v_fma_f32 v95, -v90, v96, 1.0
	v_fma_f32 v87, v95, v96, v96
	v_mul_f32_e32 v90, v87, v100
	v_cndmask_b32_e64 v87, v90, v87, s[40:41]
	v_add_f32_e32 v90, 1.0, v91
	v_mul_f32_e32 v87, v87, v80
	v_rcp_f32_e32 v92, v90
	s_nop 0
	v_fma_f32 v95, -v90, v92, 1.0
	v_fma_f32 v80, v95, v92, v92
	v_mul_f32_e32 v85, v80, v85
	v_cndmask_b32_e64 v80, v85, v80, s[40:41]
	v_mul_f32_e32 v81, v80, v81
	v_cvt_pk_bf16_f32 v80, v86, v84
	v_cvt_pk_bf16_f32 v81, v87, v81
	global_store_dwordx2 v[72:73], v[80:81], off offset:160
	v_bfe_u32 v84, v161, 4, 2
	v_lshlrev_b32_e32 v84, 4, v84
	v_add_u32_e32 v84, 0x25a80, v84
	ds_read_b128 v[84:87], v84 offset:384
	v_lshlrev_b32_e32 v80, 16, v76
	v_mul_f32_e32 v81, 0xbfb8aa3b, v80
	v_exp_f32_e32 v81, v81
	v_and_b32_e32 v76, 0xffff0000, v76
	v_lshlrev_b32_e32 v92, 16, v77
	v_and_b32_e32 v77, 0xffff0000, v77
	v_add_f32_e32 v81, 1.0, v81
	s_waitcnt lgkmcnt(0)
	v_mul_f32_e32 v86, v86, v89
	v_mul_f32_e32 v91, 0xbfb8aa3b, v76
	v_exp_f32_e32 v91, v91
	v_rcp_f32_e32 v90, v81
	s_nop 0
	v_fma_f32 v94, -v81, v90, 1.0
	v_fma_f32 v81, v94, v90, v90
	v_mul_f32_e32 v80, v81, v80
	v_cndmask_b32_e64 v80, v80, v81, s[40:41]
	v_add_f32_e32 v81, 1.0, v91
	v_mul_f32_e32 v93, v98, v0
	v_mul_f32_e32 v84, v84, v93
	v_mul_f32_e32 v80, v80, v84
	v_mul_f32_e32 v90, 0xbfb8aa3b, v92
	v_exp_f32_e32 v90, v90
	v_rcp_f32_e32 v94, v81
	s_nop 0
	v_fma_f32 v91, -v81, v94, 1.0
	v_fma_f32 v81, v91, v94, v94
	v_mul_f32_e32 v76, v81, v76
	v_cndmask_b32_e64 v76, v76, v81, s[40:41]
	v_add_f32_e32 v81, 1.0, v90
	v_mul_f32_e32 v91, v99, v0
	v_mul_f32_e32 v85, v85, v91
	v_mul_f32_e32 v76, v76, v85
	v_mul_f32_e32 v85, 0xbfb8aa3b, v77
	v_exp_f32_e32 v85, v85
	v_rcp_f32_e32 v84, v81
	s_nop 0
	v_fma_f32 v93, -v81, v84, 1.0
	v_fma_f32 v81, v93, v84, v84
	v_mul_f32_e32 v84, v81, v92
	v_cndmask_b32_e64 v81, v84, v81, s[40:41]
	v_add_f32_e32 v84, 1.0, v85
	v_mul_f32_e32 v81, v81, v86
	v_cvt_pk_bf16_f32 v76, v80, v76
	v_rcp_f32_e32 v85, v84
	s_nop 0
	v_fma_f32 v89, -v84, v85, 1.0
	v_fma_f32 v84, v89, v85, v85
	v_mul_f32_e32 v77, v84, v77
	v_cndmask_b32_e64 v77, v77, v84, s[40:41]
	v_mul_f32_e32 v84, v88, v0
	v_mul_f32_e32 v84, v87, v84
	v_mul_f32_e32 v77, v77, v84
	v_cvt_pk_bf16_f32 v77, v81, v77
	global_store_dwordx2 v[72:73], v[76:77], off offset:192
	v_bfe_u32 v84, v161, 4, 2
	v_lshlrev_b32_e32 v84, 4, v84
	v_add_u32_e32 v84, 0x25a80, v84
	ds_read_b128 v[84:87], v84 offset:448
	v_lshlrev_b32_e32 v76, 16, v74
	v_mul_f32_e32 v77, 0xbfb8aa3b, v76
	v_exp_f32_e32 v77, v77
	v_and_b32_e32 v74, 0xffff0000, v74
	v_lshlrev_b32_e32 v88, 16, v75
	v_and_b32_e32 v75, 0xffff0000, v75
	v_add_f32_e32 v77, 1.0, v77
	v_mul_f32_e32 v0, v78, v0
	v_mul_f32_e32 v81, 0xbfb8aa3b, v74
	v_exp_f32_e32 v81, v81
	v_rcp_f32_e32 v80, v77
	s_nop 0
	v_fma_f32 v90, -v77, v80, 1.0
	v_fma_f32 v77, v90, v80, v80
	v_mul_f32_e32 v76, v77, v76
	v_cndmask_b32_e64 v76, v76, v77, s[40:41]
	v_add_f32_e32 v77, 1.0, v81
	s_waitcnt lgkmcnt(0)
	v_mul_f32_e32 v83, v84, v83
	v_mul_f32_e32 v76, v76, v83
	v_mul_f32_e32 v81, 0xbfb8aa3b, v88
	v_exp_f32_e32 v81, v81
	v_rcp_f32_e32 v80, v77
	s_nop 0
	v_fma_f32 v89, -v77, v80, 1.0
	v_fma_f32 v77, v89, v80, v80
	v_mul_f32_e32 v74, v77, v74
	v_cndmask_b32_e64 v74, v74, v77, s[40:41]
	v_add_f32_e32 v77, 1.0, v81
	v_mul_f32_e32 v82, v85, v82
	v_mul_f32_e32 v74, v74, v82
	v_mul_f32_e32 v79, v86, v79
	v_mul_f32_e32 v81, 0xbfb8aa3b, v75
	v_exp_f32_e32 v81, v81
	v_rcp_f32_e32 v80, v77
	s_nop 0
	v_fma_f32 v83, -v77, v80, 1.0
	v_fma_f32 v77, v83, v80, v80
	v_mul_f32_e32 v80, v77, v88
	v_cndmask_b32_e64 v77, v80, v77, s[40:41]
	v_add_f32_e32 v80, 1.0, v81
	v_mul_f32_e32 v77, v77, v79
	v_mul_f32_e32 v0, v87, v0
	v_cvt_pk_bf16_f32 v74, v76, v74
	v_rcp_f32_e32 v83, v80
	s_nop 0
	v_fma_f32 v84, -v80, v83, 1.0
	v_fma_f32 v79, v84, v83, v83
	v_mul_f32_e32 v75, v79, v75
	v_cndmask_b32_e64 v75, v75, v79, s[40:41]
	v_mul_f32_e32 v0, v75, v0
	v_cvt_pk_bf16_f32 v75, v77, v0
	global_store_dwordx2 v[72:73], v[74:75], off offset:224
	s_branch .LBB0_97
